# up-GEMM K-loop: LDS-DMA tile loads issued between the MFMAs of their quarter instead of in the LDS-read segment, vmcnt waits re-derived 6/2/6/2
# baseline (speedup 1.0000x reference)
; #define PG8_STAGE(bufoff, gbase, voff) do { _Pragma("unroll") for (int _i = 0; _i < 2; ++_i) \
;         __builtin_amdgcn_global_load_lds((const unsigned*)((const char*)(gbase) + (voff)[_i]), (LAS unsigned*)(lds + (bufoff) + ldsw + _i * 8192), 16, 0, 0); } while (0)
; #define PG8_LDA(dst, b, h) do { _Pragma("unroll") for (int m = 0; m < 4; ++m) _Pragma("unroll") for (int k = 0; k < 2; ++k) dst[m][k] = *(const LAS bf16x8*)(lds + PG8_SA(b, h) + aoff + m * 2048 + k * 1024); } while (0)
; #define PG8_LDB(dst, b, h) do { _Pragma("unroll") for (int n = 0; n < 2; ++n) _Pragma("unroll") for (int k = 0; k < 2; ++k) dst[n][k] = *(const LAS bf16x8*)(lds + PG8_SB(b, h) + boff + n * 2048 + k * 1024); } while (0)
; #define PG8_MMA(ai, bj, At, Bt) do { __builtin_amdgcn_s_setprio(1); _Pragma("unroll") for (int m = 0; m < 4; ++m) _Pragma("unroll") for (int n = 0; n < 2; ++n) _Pragma("unroll") for (int k = 0; k < 2; ++k) \
;         acc[ai][bj][m][n] = __builtin_amdgcn_mfma_f32_16x16x32_bf16(Bt[n][k], At[m][k], acc[ai][bj][m][n], 0, 0, 0); __builtin_amdgcn_s_setprio(0); } while (0)
; #define PG8_WAIT_V(n) asm volatile("s_waitcnt vmcnt(" #n ")" ::: "memory")
; #define PG8_WAIT_L(n) asm volatile("s_waitcnt lgkmcnt(" #n ")" ::: "memory")
; #define PG8_BAR __builtin_amdgcn_s_barrier()
; #define PG8_SCHED __builtin_amdgcn_sched_barrier(0)
; template <class Epi, class Sched, bool ALIGN_EPI = false, bool SP2 = false>
; DI void gemm_phase(LAS unsigned char* lds, const Gemm g, const Sched& S, const Epi& E, const int tidx) {
;     ...
;             PG8_LDB(B0, 0, 0); PG8_LDB(B1, 0, 1); PG8_SCHED; PG8_LDA(At, 0, 0); PG8_STAGE(PG8_SA(1, 1), a1 + hstepA, voffA);
;             PG8_WAIT_V(8); PG8_WAIT_L(0); PG8_BAR; PG8_MMA(0, 0, At, B0); PG8_MMA(0, 1, At, B1); PG8_BAR; PG8_SCHED;
;             PG8_LDA(At, 0, 1); PG8_STAGE(PG8_SB(0, 0), b2, voffB); PG8_STAGE(PG8_SB(0, 1), b2 + hstepB, voffB); PG8_STAGE(PG8_SA(0, 0), a2, voffA);
;             PG8_WAIT_V(8); PG8_WAIT_L(0); PG8_BAR; PG8_MMA(1, 0, At, B0); PG8_MMA(1, 1, At, B1); PG8_BAR; PG8_SCHED;
.LBB0_159:
	s_add_u32 s22, s20, 0xfff80080
	s_addc_u32 s23, s21, -1
	s_add_i32 s83, 0, 0x10000
	s_cmp_eq_u32 s82, 28
	s_cselect_b32 s25, s13, s23
	s_cselect_b32 s24, s54, s22
	v_add_u32_e32 v138, s83, v141
	s_cselect_b32 s23, s11, s57
	s_cselect_b32 s22, s55, s56
	s_add_i32 s91, 0, 0x14000
	ds_read_b128 v[146:149], v138
	ds_read_b128 v[150:153], v138 offset:1024
	ds_read_b128 v[154:157], v138 offset:2048
	ds_read_b128 v[158:161], v138 offset:3072
	v_add_u32_e32 v138, s91, v141
	ds_read_b128 v[162:165], v138
	ds_read_b128 v[166:169], v138 offset:1024
	ds_read_b128 v[170:173], v138 offset:2048
	ds_read_b128 v[174:177], v138 offset:3072
	ds_read_b128 v[178:181], v145
	ds_read_b128 v[182:185], v145 offset:1024
	ds_read_b128 v[186:189], v145 offset:2048
	ds_read_b128 v[190:193], v145 offset:3072
	ds_read_b128 v[194:197], v145 offset:4096
	ds_read_b128 v[198:201], v145 offset:5120
	ds_read_b128 v[222:225], v145 offset:6144
	ds_read_b128 v[226:229], v145 offset:7168
	s_waitcnt vmcnt(6)
	s_waitcnt lgkmcnt(0)
	s_barrier
	s_setprio 1
	s_waitcnt lgkmcnt(0)
	v_mfma_f32_16x16x32_bf16 v[124:127], v[146:149], v[178:181], v[124:127]
	v_mfma_f32_16x16x32_bf16 v[120:123], v[154:157], v[178:181], v[120:123]
	v_mfma_f32_16x16x32_bf16 v[108:111], v[146:149], v[186:189], v[108:111]
	v_mfma_f32_16x16x32_bf16 v[104:107], v[154:157], v[186:189], v[104:107]
	v_mfma_f32_16x16x32_bf16 v[92:95], v[146:149], v[194:197], v[92:95]
	v_mfma_f32_16x16x32_bf16 v[88:91], v[154:157], v[194:197], v[88:91]
	v_mfma_f32_16x16x32_bf16 v[76:79], v[146:149], v[222:225], v[76:79]
	v_mfma_f32_16x16x32_bf16 v[72:75], v[154:157], v[222:225], v[72:75]
	v_lshl_add_u64 v[202:203], s[20:21], 0, v[134:135]
	s_add_i32 m0, s30, 0xc000
	s_nop 0
	global_load_lds_dwordx4 v[202:203], off
	v_mfma_f32_16x16x32_bf16 v[124:127], v[150:153], v[182:185], v[124:127]
	v_mfma_f32_16x16x32_bf16 v[120:123], v[158:161], v[182:185], v[120:123]
	v_mfma_f32_16x16x32_bf16 v[108:111], v[150:153], v[190:193], v[108:111]
	v_mfma_f32_16x16x32_bf16 v[104:107], v[158:161], v[190:193], v[104:107]
	v_mfma_f32_16x16x32_bf16 v[92:95], v[150:153], v[198:201], v[92:95]
	v_mfma_f32_16x16x32_bf16 v[88:91], v[158:161], v[198:201], v[88:91]
	v_mfma_f32_16x16x32_bf16 v[76:79], v[150:153], v[226:229], v[76:79]
	v_mfma_f32_16x16x32_bf16 v[72:75], v[158:161], v[226:229], v[72:75]
	s_setprio 0
	s_setprio 1
	v_mfma_f32_16x16x32_bf16 v[116:119], v[162:165], v[178:181], v[116:119]
	v_mfma_f32_16x16x32_bf16 v[112:115], v[170:173], v[178:181], v[112:115]
	v_mfma_f32_16x16x32_bf16 v[100:103], v[162:165], v[186:189], v[100:103]
	v_mfma_f32_16x16x32_bf16 v[96:99], v[170:173], v[186:189], v[96:99]
	v_mfma_f32_16x16x32_bf16 v[84:87], v[162:165], v[194:197], v[84:87]
	v_mfma_f32_16x16x32_bf16 v[80:83], v[170:173], v[194:197], v[80:83]
	v_mfma_f32_16x16x32_bf16 v[68:71], v[162:165], v[222:225], v[68:71]
	v_mfma_f32_16x16x32_bf16 v[64:67], v[170:173], v[222:225], v[64:67]
	v_lshl_add_u64 v[202:203], s[20:21], 0, v[136:137]
	s_add_i32 m0, s30, 0xe000
	s_nop 0
	global_load_lds_dwordx4 v[202:203], off
	v_mfma_f32_16x16x32_bf16 v[116:119], v[166:169], v[182:185], v[116:119]
	v_mfma_f32_16x16x32_bf16 v[112:115], v[174:177], v[182:185], v[112:115]
	v_mfma_f32_16x16x32_bf16 v[100:103], v[166:169], v[190:193], v[100:103]
	v_mfma_f32_16x16x32_bf16 v[96:99], v[174:177], v[190:193], v[96:99]
	v_mfma_f32_16x16x32_bf16 v[84:87], v[166:169], v[198:201], v[84:87]
	v_mfma_f32_16x16x32_bf16 v[80:83], v[174:177], v[198:201], v[80:83]
	v_mfma_f32_16x16x32_bf16 v[68:71], v[166:169], v[226:229], v[68:71]
	v_mfma_f32_16x16x32_bf16 v[64:67], v[174:177], v[226:229], v[64:67]
	s_setprio 0
	s_barrier
	ds_read_b128 v[178:181], v145 offset:16384
	ds_read_b128 v[182:185], v145 offset:17408
	ds_read_b128 v[186:189], v145 offset:18432
	ds_read_b128 v[190:193], v145 offset:19456
	ds_read_b128 v[194:197], v145 offset:20480
	ds_read_b128 v[198:201], v145 offset:21504
	ds_read_b128 v[222:225], v145 offset:22528
	ds_read_b128 v[226:229], v145 offset:23552
	s_waitcnt vmcnt(2)
	s_waitcnt lgkmcnt(0)
	s_barrier
	s_setprio 1
	s_waitcnt lgkmcnt(0)
	v_mfma_f32_16x16x32_bf16 v[60:63], v[146:149], v[178:181], v[60:63]
	v_mfma_f32_16x16x32_bf16 v[56:59], v[154:157], v[178:181], v[56:59]
	v_mfma_f32_16x16x32_bf16 v[44:47], v[146:149], v[186:189], v[44:47]
	v_mfma_f32_16x16x32_bf16 v[40:43], v[154:157], v[186:189], v[40:43]
	s_add_i32 s83, s83, s29
	v_lshl_add_u64 v[202:203], s[22:23], 0, v[204:205]
	s_mov_b32 m0, s83
	s_nop 0
	global_load_lds_dwordx4 v[202:203], off
	v_mfma_f32_16x16x32_bf16 v[28:31], v[146:149], v[194:197], v[28:31]
	v_mfma_f32_16x16x32_bf16 v[24:27], v[154:157], v[194:197], v[24:27]
	v_mfma_f32_16x16x32_bf16 v[12:15], v[146:149], v[222:225], v[12:15]
	v_mfma_f32_16x16x32_bf16 v[8:11], v[154:157], v[222:225], v[8:11]
	s_add_i32 m0, s83, 0x2000
	s_add_u32 vcc_lo, s22, 0x80000
	v_lshl_add_u64 v[206:207], s[22:23], 0, v[132:133]
	s_addc_u32 vcc_hi, s23, 0
	s_add_i32 s83, s91, s29
	global_load_lds_dwordx4 v[206:207], off
	v_mfma_f32_16x16x32_bf16 v[60:63], v[150:153], v[182:185], v[60:63]
	v_mfma_f32_16x16x32_bf16 v[56:59], v[158:161], v[182:185], v[56:59]
	v_mfma_f32_16x16x32_bf16 v[44:47], v[150:153], v[190:193], v[44:47]
	v_mfma_f32_16x16x32_bf16 v[40:43], v[158:161], v[190:193], v[40:43]
	v_lshl_add_u64 v[208:209], vcc, 0, v[204:205]
	s_mov_b32 m0, s83
	v_lshl_add_u64 v[230:231], s[24:25], 0, v[130:131]
	global_load_lds_dwordx4 v[208:209], off
	v_mfma_f32_16x16x32_bf16 v[28:31], v[150:153], v[198:201], v[28:31]
	v_mfma_f32_16x16x32_bf16 v[24:27], v[158:161], v[198:201], v[24:27]
	v_mfma_f32_16x16x32_bf16 v[12:15], v[150:153], v[226:229], v[12:15]
; #define PG8_STAGE(bufoff, gbase, voff) do { _Pragma("unroll") for (int _i = 0; _i < 2; ++_i) \
;         __builtin_amdgcn_global_load_lds((const unsigned*)((const char*)(gbase) + (voff)[_i]), (LAS unsigned*)(lds + (bufoff) + ldsw + _i * 8192), 16, 0, 0); } while (0)
; #define PG8_LDA(dst, b, h) do { _Pragma("unroll") for (int m = 0; m < 4; ++m) _Pragma("unroll") for (int k = 0; k < 2; ++k) dst[m][k] = *(const LAS bf16x8*)(lds + PG8_SA(b, h) + aoff + m * 2048 + k * 1024); } while (0)
; #define PG8_LDB(dst, b, h) do { _Pragma("unroll") for (int n = 0; n < 2; ++n) _Pragma("unroll") for (int k = 0; k < 2; ++k) dst[n][k] = *(const LAS bf16x8*)(lds + PG8_SB(b, h) + boff + n * 2048 + k * 1024); } while (0)
; #define PG8_MMA(ai, bj, At, Bt) do { __builtin_amdgcn_s_setprio(1); _Pragma("unroll") for (int m = 0; m < 4; ++m) _Pragma("unroll") for (int n = 0; n < 2; ++n) _Pragma("unroll") for (int k = 0; k < 2; ++k) \
;         acc[ai][bj][m][n] = __builtin_amdgcn_mfma_f32_16x16x32_bf16(Bt[n][k], At[m][k], acc[ai][bj][m][n], 0, 0, 0); __builtin_amdgcn_s_setprio(0); } while (0)
; #define PG8_WAIT_V(n) asm volatile("s_waitcnt vmcnt(" #n ")" ::: "memory")
; #define PG8_WAIT_L(n) asm volatile("s_waitcnt lgkmcnt(" #n ")" ::: "memory")
; #define PG8_BAR __builtin_amdgcn_s_barrier()
; #define PG8_SCHED __builtin_amdgcn_sched_barrier(0)
; template <class Epi, class Sched, bool ALIGN_EPI = false, bool SP2 = false>
; DI void gemm_phase(LAS unsigned char* lds, const Gemm g, const Sched& S, const Epi& E, const int tidx) {
;     ...
;             PG8_WAIT_V(8); PG8_WAIT_L(0); PG8_BAR; PG8_MMA(1, 0, At, B0); PG8_MMA(1, 1, At, B1); PG8_BAR; PG8_SCHED;
;             PG8_LDB(B0, 1, 0); PG8_LDB(B1, 1, 1); PG8_SCHED; PG8_LDA(At, 1, 0); PG8_STAGE(PG8_SA(0, 1), a2 + hstepA, voffA);
;             PG8_WAIT_V(8); PG8_WAIT_L(0); PG8_BAR; PG8_MMA(0, 0, At, B0); PG8_MMA(0, 1, At, B1); PG8_BAR; PG8_SCHED;
;             PG8_LDA(At, 1, 1); PG8_STAGE(PG8_SB(1, 0), b3, voffB); PG8_STAGE(PG8_SB(1, 1), b3 + hstepB, voffB); PG8_STAGE(PG8_SA(1, 0), a3, voffA);
	v_mfma_f32_16x16x32_bf16 v[8:11], v[158:161], v[226:229], v[8:11]
	s_setprio 0
	s_setprio 1
	v_lshl_add_u64 v[208:209], vcc, 0, v[132:133]
	s_add_i32 m0, s83, 0x2000
	s_nop 0
	global_load_lds_dwordx4 v[208:209], off
	v_mfma_f32_16x16x32_bf16 v[52:55], v[162:165], v[178:181], v[52:55]
	v_mfma_f32_16x16x32_bf16 v[48:51], v[170:173], v[178:181], v[48:51]
	v_mfma_f32_16x16x32_bf16 v[36:39], v[162:165], v[186:189], v[36:39]
	v_mfma_f32_16x16x32_bf16 v[32:35], v[170:173], v[186:189], v[32:35]
	v_lshl_add_u64 v[208:209], s[24:25], 0, v[128:129]
	s_mov_b32 m0, s30
	s_nop 0
	global_load_lds_dwordx4 v[208:209], off
	v_mfma_f32_16x16x32_bf16 v[20:23], v[162:165], v[194:197], v[20:23]
	v_mfma_f32_16x16x32_bf16 v[16:19], v[170:173], v[194:197], v[16:19]
	v_mfma_f32_16x16x32_bf16 v[4:7], v[162:165], v[222:225], v[4:7]
	v_mfma_f32_16x16x32_bf16 v[0:3], v[170:173], v[222:225], v[0:3]
	s_mov_b32 m0, s31
	s_nop 0
	global_load_lds_dwordx4 v[230:231], off
	v_mfma_f32_16x16x32_bf16 v[52:55], v[166:169], v[182:185], v[52:55]
	v_mfma_f32_16x16x32_bf16 v[48:51], v[174:177], v[182:185], v[48:51]
	v_mfma_f32_16x16x32_bf16 v[36:39], v[166:169], v[190:193], v[36:39]
	v_mfma_f32_16x16x32_bf16 v[32:35], v[174:177], v[190:193], v[32:35]
	v_mfma_f32_16x16x32_bf16 v[20:23], v[166:169], v[198:201], v[20:23]
	v_mfma_f32_16x16x32_bf16 v[16:19], v[174:177], v[198:201], v[16:19]
	v_mfma_f32_16x16x32_bf16 v[4:7], v[166:169], v[226:229], v[4:7]
	v_mfma_f32_16x16x32_bf16 v[0:3], v[174:177], v[226:229], v[0:3]
	s_setprio 0
	s_barrier
	s_add_i32 s83, 0, 0x18000
	v_add_u32_e32 v138, s83, v141
	s_add_i32 s91, 0, 0x1c000
	ds_read_b128 v[146:149], v138
	ds_read_b128 v[150:153], v138 offset:1024
	ds_read_b128 v[154:157], v138 offset:2048
	ds_read_b128 v[158:161], v138 offset:3072
	v_add_u32_e32 v138, s91, v141
	ds_read_b128 v[162:165], v138
	ds_read_b128 v[166:169], v138 offset:1024
	ds_read_b128 v[170:173], v138 offset:2048
	ds_read_b128 v[174:177], v138 offset:3072
	ds_read_b128 v[178:181], v145 offset:32768
	ds_read_b128 v[182:185], v145 offset:33792
	ds_read_b128 v[186:189], v145 offset:34816
	ds_read_b128 v[190:193], v145 offset:35840
	ds_read_b128 v[194:197], v145 offset:36864
	ds_read_b128 v[198:201], v145 offset:37888
	ds_read_b128 v[222:225], v145 offset:38912
	ds_read_b128 v[226:229], v145 offset:39936
	s_waitcnt vmcnt(6)
	s_waitcnt lgkmcnt(0)
	s_barrier
	s_setprio 1
	s_waitcnt lgkmcnt(0)
	v_mfma_f32_16x16x32_bf16 v[124:127], v[146:149], v[178:181], v[124:127]
	v_mfma_f32_16x16x32_bf16 v[120:123], v[154:157], v[178:181], v[120:123]
	v_mfma_f32_16x16x32_bf16 v[108:111], v[146:149], v[186:189], v[108:111]
	v_mfma_f32_16x16x32_bf16 v[104:107], v[154:157], v[186:189], v[104:107]
	v_mfma_f32_16x16x32_bf16 v[92:95], v[146:149], v[194:197], v[92:95]
	v_mfma_f32_16x16x32_bf16 v[88:91], v[154:157], v[194:197], v[88:91]
	v_mfma_f32_16x16x32_bf16 v[76:79], v[146:149], v[222:225], v[76:79]
	v_mfma_f32_16x16x32_bf16 v[72:75], v[154:157], v[222:225], v[72:75]
	s_add_u32 s24, s24, 0x80000
	s_addc_u32 s25, s25, 0
	s_mov_b32 m0, s34
	v_lshl_add_u64 v[232:233], s[24:25], 0, v[128:129]
	global_load_lds_dwordx4 v[232:233], off
	v_mfma_f32_16x16x32_bf16 v[124:127], v[150:153], v[182:185], v[124:127]
	v_mfma_f32_16x16x32_bf16 v[120:123], v[158:161], v[182:185], v[120:123]
	v_mfma_f32_16x16x32_bf16 v[108:111], v[150:153], v[190:193], v[108:111]
	v_mfma_f32_16x16x32_bf16 v[104:107], v[158:161], v[190:193], v[104:107]
	v_mfma_f32_16x16x32_bf16 v[92:95], v[150:153], v[198:201], v[92:95]
	v_mfma_f32_16x16x32_bf16 v[88:91], v[158:161], v[198:201], v[88:91]
	v_mfma_f32_16x16x32_bf16 v[76:79], v[150:153], v[226:229], v[76:79]
	v_mfma_f32_16x16x32_bf16 v[72:75], v[158:161], v[226:229], v[72:75]
	s_setprio 0
	s_setprio 1
	v_mfma_f32_16x16x32_bf16 v[116:119], v[162:165], v[178:181], v[116:119]
	v_mfma_f32_16x16x32_bf16 v[112:115], v[170:173], v[178:181], v[112:115]
	v_mfma_f32_16x16x32_bf16 v[100:103], v[162:165], v[186:189], v[100:103]
	v_mfma_f32_16x16x32_bf16 v[96:99], v[170:173], v[186:189], v[96:99]
	v_mfma_f32_16x16x32_bf16 v[84:87], v[162:165], v[194:197], v[84:87]
	v_mfma_f32_16x16x32_bf16 v[80:83], v[170:173], v[194:197], v[80:83]
	v_mfma_f32_16x16x32_bf16 v[68:71], v[162:165], v[222:225], v[68:71]
	v_mfma_f32_16x16x32_bf16 v[64:67], v[170:173], v[222:225], v[64:67]
	v_lshl_add_u64 v[232:233], s[24:25], 0, v[130:131]
	s_mov_b32 m0, s35
	s_nop 0
	global_load_lds_dwordx4 v[232:233], off
	v_mfma_f32_16x16x32_bf16 v[116:119], v[166:169], v[182:185], v[116:119]
	v_mfma_f32_16x16x32_bf16 v[112:115], v[174:177], v[182:185], v[112:115]
	v_mfma_f32_16x16x32_bf16 v[100:103], v[166:169], v[190:193], v[100:103]
	v_mfma_f32_16x16x32_bf16 v[96:99], v[174:177], v[190:193], v[96:99]
	v_mfma_f32_16x16x32_bf16 v[84:87], v[166:169], v[198:201], v[84:87]
	v_mfma_f32_16x16x32_bf16 v[80:83], v[174:177], v[198:201], v[80:83]
	v_mfma_f32_16x16x32_bf16 v[68:71], v[166:169], v[226:229], v[68:71]
	v_mfma_f32_16x16x32_bf16 v[64:67], v[174:177], v[226:229], v[64:67]
	s_setprio 0
	s_barrier
; #define PG8_STAGE(bufoff, gbase, voff) do { _Pragma("unroll") for (int _i = 0; _i < 2; ++_i) \
;         __builtin_amdgcn_global_load_lds((const unsigned*)((const char*)(gbase) + (voff)[_i]), (LAS unsigned*)(lds + (bufoff) + ldsw + _i * 8192), 16, 0, 0); } while (0)
; #define PG8_LDA(dst, b, h) do { _Pragma("unroll") for (int m = 0; m < 4; ++m) _Pragma("unroll") for (int k = 0; k < 2; ++k) dst[m][k] = *(const LAS bf16x8*)(lds + PG8_SA(b, h) + aoff + m * 2048 + k * 1024); } while (0)
; #define PG8_MMA(ai, bj, At, Bt) do { __builtin_amdgcn_s_setprio(1); _Pragma("unroll") for (int m = 0; m < 4; ++m) _Pragma("unroll") for (int n = 0; n < 2; ++n) _Pragma("unroll") for (int k = 0; k < 2; ++k) \
;         acc[ai][bj][m][n] = __builtin_amdgcn_mfma_f32_16x16x32_bf16(Bt[n][k], At[m][k], acc[ai][bj][m][n], 0, 0, 0); __builtin_amdgcn_s_setprio(0); } while (0)
; #define PG8_WAIT_V(n) asm volatile("s_waitcnt vmcnt(" #n ")" ::: "memory")
; #define PG8_WAIT_L(n) asm volatile("s_waitcnt lgkmcnt(" #n ")" ::: "memory")
; #define PG8_BAR __builtin_amdgcn_s_barrier()
; #define PG8_SCHED __builtin_amdgcn_sched_barrier(0)
; template <class Epi, class Sched, bool ALIGN_EPI = false, bool SP2 = false>
; DI void gemm_phase(LAS unsigned char* lds, const Gemm g, const Sched& S, const Epi& E, const int tidx) {
;     ...
;         for (int t = 0; t < nt; t += 2) {
;     ...
;             PG8_LDA(At, 1, 1); PG8_STAGE(PG8_SB(1, 0), b3, voffB); PG8_STAGE(PG8_SB(1, 1), b3 + hstepB, voffB); PG8_STAGE(PG8_SA(1, 0), a3, voffA);
;             PG8_WAIT_V(8); PG8_WAIT_L(0); PG8_BAR; PG8_MMA(1, 0, At, B0); PG8_MMA(1, 1, At, B1); PG8_BAR; PG8_SCHED;
	ds_read_b128 v[178:181], v145 offset:49152
	ds_read_b128 v[182:185], v145 offset:50176
	ds_read_b128 v[186:189], v145 offset:51200
	ds_read_b128 v[190:193], v145 offset:52224
	ds_read_b128 v[194:197], v145 offset:53248
	ds_read_b128 v[198:201], v145 offset:54272
	ds_read_b128 v[222:225], v145 offset:55296
	ds_read_b128 v[226:229], v145 offset:56320
	s_waitcnt vmcnt(2)
	s_waitcnt lgkmcnt(0)
	s_barrier
	s_setprio 1
	s_waitcnt lgkmcnt(0)
	v_mfma_f32_16x16x32_bf16 v[60:63], v[146:149], v[178:181], v[60:63]
	v_mfma_f32_16x16x32_bf16 v[56:59], v[154:157], v[178:181], v[56:59]
	v_mfma_f32_16x16x32_bf16 v[44:47], v[146:149], v[186:189], v[44:47]
	v_mfma_f32_16x16x32_bf16 v[40:43], v[154:157], v[186:189], v[40:43]
	s_add_i32 s24, s83, s29
	v_lshl_add_u64 v[202:203], v[202:203], 0, s[92:93]
	s_mov_b32 m0, s24
	s_nop 0
	global_load_lds_dwordx4 v[202:203], off
	v_mfma_f32_16x16x32_bf16 v[28:31], v[146:149], v[194:197], v[28:31]
	v_mfma_f32_16x16x32_bf16 v[24:27], v[154:157], v[194:197], v[24:27]
	v_mfma_f32_16x16x32_bf16 v[12:15], v[146:149], v[222:225], v[12:15]
	v_mfma_f32_16x16x32_bf16 v[8:11], v[154:157], v[222:225], v[8:11]
	s_add_i32 m0, s24, 0x2000
	s_add_u32 s22, s22, 0x80080
	v_lshl_add_u64 v[202:203], v[206:207], 0, s[92:93]
	s_addc_u32 s23, s23, 0
	s_add_i32 s24, s91, s29
	global_load_lds_dwordx4 v[202:203], off
	v_mfma_f32_16x16x32_bf16 v[60:63], v[150:153], v[182:185], v[60:63]
	v_mfma_f32_16x16x32_bf16 v[56:59], v[158:161], v[182:185], v[56:59]
	v_mfma_f32_16x16x32_bf16 v[44:47], v[150:153], v[190:193], v[44:47]
	v_mfma_f32_16x16x32_bf16 v[40:43], v[158:161], v[190:193], v[40:43]
	v_lshl_add_u64 v[202:203], s[22:23], 0, v[204:205]
	s_mov_b32 m0, s24
	s_nop 0
	global_load_lds_dwordx4 v[202:203], off
	v_mfma_f32_16x16x32_bf16 v[28:31], v[150:153], v[198:201], v[28:31]
	v_mfma_f32_16x16x32_bf16 v[24:27], v[158:161], v[198:201], v[24:27]
	v_mfma_f32_16x16x32_bf16 v[12:15], v[150:153], v[226:229], v[12:15]
	v_mfma_f32_16x16x32_bf16 v[8:11], v[158:161], v[226:229], v[8:11]
	s_setprio 0
	s_setprio 1
	v_lshl_add_u64 v[202:203], s[22:23], 0, v[132:133]
	s_add_i32 m0, s24, 0x2000
	s_nop 0
	global_load_lds_dwordx4 v[202:203], off
	v_mfma_f32_16x16x32_bf16 v[52:55], v[162:165], v[178:181], v[52:55]
	v_mfma_f32_16x16x32_bf16 v[48:51], v[170:173], v[178:181], v[48:51]
	v_mfma_f32_16x16x32_bf16 v[36:39], v[162:165], v[186:189], v[36:39]
	v_mfma_f32_16x16x32_bf16 v[32:35], v[170:173], v[186:189], v[32:35]
	v_lshl_add_u64 v[202:203], v[208:209], 0, s[92:93]
	s_mov_b32 m0, s36
	s_nop 0
	global_load_lds_dwordx4 v[202:203], off
	v_mfma_f32_16x16x32_bf16 v[20:23], v[162:165], v[194:197], v[20:23]
	v_mfma_f32_16x16x32_bf16 v[16:19], v[170:173], v[194:197], v[16:19]
	v_mfma_f32_16x16x32_bf16 v[4:7], v[162:165], v[222:225], v[4:7]
	v_mfma_f32_16x16x32_bf16 v[0:3], v[170:173], v[222:225], v[0:3]
	v_lshl_add_u64 v[202:203], v[230:231], 0, s[92:93]
	s_mov_b32 m0, s37
	s_nop 0
	global_load_lds_dwordx4 v[202:203], off
	v_mfma_f32_16x16x32_bf16 v[52:55], v[166:169], v[182:185], v[52:55]
	v_mfma_f32_16x16x32_bf16 v[48:51], v[174:177], v[182:185], v[48:51]
	v_mfma_f32_16x16x32_bf16 v[36:39], v[166:169], v[190:193], v[36:39]
	v_mfma_f32_16x16x32_bf16 v[32:35], v[174:177], v[190:193], v[32:35]
	v_mfma_f32_16x16x32_bf16 v[20:23], v[166:169], v[198:201], v[20:23]
	v_mfma_f32_16x16x32_bf16 v[16:19], v[174:177], v[198:201], v[16:19]
	v_mfma_f32_16x16x32_bf16 v[4:7], v[166:169], v[226:229], v[4:7]
	v_mfma_f32_16x16x32_bf16 v[0:3], v[174:177], v[226:229], v[0:3]
	s_setprio 0
	s_barrier
	s_add_i32 s82, s82, 2
	s_add_u32 s56, s56, 0x100
	s_addc_u32 s57, s57, 0
	s_add_u32 s20, s20, 0x100
	s_addc_u32 s21, s21, 0
	s_cmp_gt_u32 s82, 29
	s_cbranch_scc0 .LBB0_159
	s_and_b64 vcc, exec, s[6:7]
	s_cbranch_vccz .LBB0_162
	s_barrier
